# retention intra-chunk decay block: exponent per element by one v_fmamk pair + min (exp2(min(cb*t,-cf*t))) instead of abs/select/convert/multiply; packed bf16 converts
# baseline (speedup 1.0000x reference)
.LBB0_1213:
	s_andn2_b64 vcc, exec, s[22:23]
	s_cbranch_vccnz .LBB0_1215
	v_add_u32_e32 v14, v2, v226
	v_or_b32_e32 v3, v242, v227
	v_or_b32_e32 v180, 1, v14
	v_or_b32_e32 v182, 2, v14
	v_or_b32_e32 v184, 3, v14
	v_add_u32_e32 v186, 8, v14
	v_add_u32_e32 v188, 9, v14
	v_add_u32_e32 v190, 10, v14
	v_add_u32_e32 v192, 11, v14
	v_add_u32_e32 v194, 16, v14
	v_add_u32_e32 v196, 17, v14
	v_add_u32_e32 v198, 18, v14
	v_add_u32_e32 v200, 19, v14
	v_add_u32_e32 v202, 24, v14
	v_add_u32_e32 v204, 25, v14
	v_add_u32_e32 v206, 26, v14
	v_add_u32_e32 v208, 27, v14
	v_sub_u32_e32 v4, v3, v14
	v_lshlrev_b32_e32 v5, 1, v3
	v_cvt_f32_i32_e32 v4, v4
	v_mul_lo_u32 v1, v14, s33
	v_mul_f32_e32 v212, v199, v4
	v_mul_f32_e64 v213, -v201, v4
	v_add3_u32 v1, v246, v1, v5
	v_min_f32_e32 v214, v212, v213
	v_fmamk_f32 v215, v199, 0xbf800000, v212
	v_fmamk_f32 v216, v201, 0x3f800000, v213
	v_min_f32_e32 v215, v215, v216
	v_exp_f32_e32 v214, v214
	v_exp_f32_e32 v215, v215
	s_nop 0
	v_mul_f32_e32 v214, v214, v128
	v_mul_f32_e32 v215, v215, v129
	v_cvt_pk_bf16_f32 v217, v214, v215
	ds_write_b16 v1, v217
	ds_write_b16_d16_hi v1, v217 offset:272
	v_fmamk_f32 v214, v199, 0xc0000000, v212
	v_fmamk_f32 v216, v201, 0x40000000, v213
	v_min_f32_e32 v214, v214, v216
	v_fmamk_f32 v215, v199, 0xc0400000, v212
	v_fmamk_f32 v216, v201, 0x40400000, v213
	v_min_f32_e32 v215, v215, v216
	v_exp_f32_e32 v214, v214
	v_exp_f32_e32 v215, v215
	s_nop 0
	v_mul_f32_e32 v214, v214, v130
	v_mul_f32_e32 v215, v215, v131
	v_cvt_pk_bf16_f32 v217, v214, v215
	ds_write_b16 v1, v217 offset:544
	ds_write_b16_d16_hi v1, v217 offset:816
	v_fmamk_f32 v214, v199, 0xc1000000, v212
	v_fmamk_f32 v216, v201, 0x41000000, v213
	v_min_f32_e32 v214, v214, v216
	v_fmamk_f32 v215, v199, 0xc1100000, v212
	v_fmamk_f32 v216, v201, 0x41100000, v213
	v_min_f32_e32 v215, v215, v216
	v_exp_f32_e32 v214, v214
	v_exp_f32_e32 v215, v215
	s_nop 0
	v_mul_f32_e32 v214, v214, v132
	v_mul_f32_e32 v215, v215, v133
	v_cvt_pk_bf16_f32 v217, v214, v215
	ds_write_b16 v1, v217 offset:2176
	ds_write_b16_d16_hi v1, v217 offset:2448
	v_fmamk_f32 v214, v199, 0xc1200000, v212
	v_fmamk_f32 v216, v201, 0x41200000, v213
	v_min_f32_e32 v214, v214, v216
	v_fmamk_f32 v215, v199, 0xc1300000, v212
	v_fmamk_f32 v216, v201, 0x41300000, v213
	v_min_f32_e32 v215, v215, v216
	v_exp_f32_e32 v214, v214
	v_exp_f32_e32 v215, v215
	s_nop 0
	v_mul_f32_e32 v214, v214, v134
	v_mul_f32_e32 v215, v215, v135
	v_cvt_pk_bf16_f32 v217, v214, v215
	ds_write_b16 v1, v217 offset:2720
	ds_write_b16_d16_hi v1, v217 offset:2992
	v_fmamk_f32 v214, v199, 0xc1800000, v212
	v_fmamk_f32 v216, v201, 0x41800000, v213
	v_min_f32_e32 v214, v214, v216
	v_fmamk_f32 v215, v199, 0xc1880000, v212
	v_fmamk_f32 v216, v201, 0x41880000, v213
	v_min_f32_e32 v215, v215, v216
	v_exp_f32_e32 v214, v214
	v_exp_f32_e32 v215, v215
	s_nop 0
	v_mul_f32_e32 v214, v214, v136
	v_mul_f32_e32 v215, v215, v137
	v_cvt_pk_bf16_f32 v217, v214, v215
	ds_write_b16 v1, v217 offset:4352
	ds_write_b16_d16_hi v1, v217 offset:4624
	v_fmamk_f32 v214, v199, 0xc1900000, v212
	v_fmamk_f32 v216, v201, 0x41900000, v213
	v_min_f32_e32 v214, v214, v216
	v_fmamk_f32 v215, v199, 0xc1980000, v212
	v_fmamk_f32 v216, v201, 0x41980000, v213
	v_min_f32_e32 v215, v215, v216
	v_exp_f32_e32 v214, v214
	v_exp_f32_e32 v215, v215
	s_nop 0
	v_mul_f32_e32 v214, v214, v138
	v_mul_f32_e32 v215, v215, v139
	v_cvt_pk_bf16_f32 v217, v214, v215
	ds_write_b16 v1, v217 offset:4896
	ds_write_b16_d16_hi v1, v217 offset:5168
	v_fmamk_f32 v214, v199, 0xc1c00000, v212
	v_fmamk_f32 v216, v201, 0x41c00000, v213
	v_min_f32_e32 v214, v214, v216
	v_fmamk_f32 v215, v199, 0xc1c80000, v212
	v_fmamk_f32 v216, v201, 0x41c80000, v213
	v_min_f32_e32 v215, v215, v216
	v_exp_f32_e32 v214, v214
	v_exp_f32_e32 v215, v215
	s_nop 0
	v_mul_f32_e32 v214, v214, v140
	v_mul_f32_e32 v215, v215, v141
	v_cvt_pk_bf16_f32 v217, v214, v215
	ds_write_b16 v1, v217 offset:6528
	ds_write_b16_d16_hi v1, v217 offset:6800
	v_fmamk_f32 v214, v199, 0xc1d00000, v212
	v_fmamk_f32 v216, v201, 0x41d00000, v213
	v_min_f32_e32 v214, v214, v216
	v_fmamk_f32 v215, v199, 0xc1d80000, v212
	v_fmamk_f32 v216, v201, 0x41d80000, v213
	v_min_f32_e32 v215, v215, v216
	v_exp_f32_e32 v214, v214
	v_exp_f32_e32 v215, v215
	s_nop 0
	v_mul_f32_e32 v214, v214, v142
	v_mul_f32_e32 v215, v215, v143
	v_cvt_pk_bf16_f32 v217, v214, v215
	ds_write_b16 v1, v217 offset:7072
	ds_write_b16_d16_hi v1, v217 offset:7344
	v_fmamk_f32 v214, v199, 0x42000000, v212
	v_fmamk_f32 v216, v201, 0xc2000000, v213
	v_min_f32_e32 v214, v214, v216
	v_fmamk_f32 v215, v199, 0x41f80000, v212
	v_fmamk_f32 v216, v201, 0xc1f80000, v213
	v_min_f32_e32 v215, v215, v216
	v_exp_f32_e32 v214, v214
	v_exp_f32_e32 v215, v215
	s_nop 0
	v_mul_f32_e32 v214, v214, v112
	v_mul_f32_e32 v215, v215, v113
	v_cvt_pk_bf16_f32 v217, v214, v215
	ds_write_b16 v1, v217 offset:64
	ds_write_b16_d16_hi v1, v217 offset:336
	v_fmamk_f32 v214, v199, 0x41f00000, v212
	v_fmamk_f32 v216, v201, 0xc1f00000, v213
	v_min_f32_e32 v214, v214, v216
	v_fmamk_f32 v215, v199, 0x41e80000, v212
	v_fmamk_f32 v216, v201, 0xc1e80000, v213
	v_min_f32_e32 v215, v215, v216
	v_exp_f32_e32 v214, v214
	v_exp_f32_e32 v215, v215
	s_nop 0
	v_mul_f32_e32 v214, v214, v114
	v_mul_f32_e32 v215, v215, v115
	v_cvt_pk_bf16_f32 v217, v214, v215
	ds_write_b16 v1, v217 offset:608
	ds_write_b16_d16_hi v1, v217 offset:880
	v_fmamk_f32 v214, v199, 0x41c00000, v212
	v_fmamk_f32 v216, v201, 0xc1c00000, v213
	v_min_f32_e32 v214, v214, v216
	v_fmamk_f32 v215, v199, 0x41b80000, v212
	v_fmamk_f32 v216, v201, 0xc1b80000, v213
	v_min_f32_e32 v215, v215, v216
	v_exp_f32_e32 v214, v214
	v_exp_f32_e32 v215, v215
	s_nop 0
	v_mul_f32_e32 v214, v214, v116
	v_mul_f32_e32 v215, v215, v117
	v_cvt_pk_bf16_f32 v217, v214, v215
	ds_write_b16 v1, v217 offset:2240
	ds_write_b16_d16_hi v1, v217 offset:2512
	v_fmamk_f32 v214, v199, 0x41b00000, v212
	v_fmamk_f32 v216, v201, 0xc1b00000, v213
	v_min_f32_e32 v214, v214, v216
	v_fmamk_f32 v215, v199, 0x41a80000, v212
	v_fmamk_f32 v216, v201, 0xc1a80000, v213
	v_min_f32_e32 v215, v215, v216
	v_exp_f32_e32 v214, v214
	v_exp_f32_e32 v215, v215
	s_nop 0
	v_mul_f32_e32 v214, v214, v118
	v_mul_f32_e32 v215, v215, v119
	v_cvt_pk_bf16_f32 v217, v214, v215
	ds_write_b16 v1, v217 offset:2784
	ds_write_b16_d16_hi v1, v217 offset:3056
	v_fmamk_f32 v214, v199, 0x41800000, v212
	v_fmamk_f32 v216, v201, 0xc1800000, v213
	v_min_f32_e32 v214, v214, v216
	v_fmamk_f32 v215, v199, 0x41700000, v212
	v_fmamk_f32 v216, v201, 0xc1700000, v213
	v_min_f32_e32 v215, v215, v216
	v_exp_f32_e32 v214, v214
	v_exp_f32_e32 v215, v215
	s_nop 0
	v_mul_f32_e32 v214, v214, v120
	v_mul_f32_e32 v215, v215, v121
	v_cvt_pk_bf16_f32 v217, v214, v215
	ds_write_b16 v1, v217 offset:4416
	ds_write_b16_d16_hi v1, v217 offset:4688
	v_fmamk_f32 v214, v199, 0x41600000, v212
	v_fmamk_f32 v216, v201, 0xc1600000, v213
	v_min_f32_e32 v214, v214, v216
	v_fmamk_f32 v215, v199, 0x41500000, v212
	v_fmamk_f32 v216, v201, 0xc1500000, v213
	v_min_f32_e32 v215, v215, v216
	v_exp_f32_e32 v214, v214
	v_exp_f32_e32 v215, v215
	s_nop 0
	v_mul_f32_e32 v214, v214, v122
	v_mul_f32_e32 v215, v215, v123
	v_cvt_pk_bf16_f32 v217, v214, v215
	ds_write_b16 v1, v217 offset:4960
	ds_write_b16_d16_hi v1, v217 offset:5232
	v_fmamk_f32 v214, v199, 0x41000000, v212
	v_fmamk_f32 v216, v201, 0xc1000000, v213
	v_min_f32_e32 v214, v214, v216
	v_fmamk_f32 v215, v199, 0x40e00000, v212
	v_fmamk_f32 v216, v201, 0xc0e00000, v213
	v_min_f32_e32 v215, v215, v216
	v_exp_f32_e32 v214, v214
	v_exp_f32_e32 v215, v215
	s_nop 0
	v_mul_f32_e32 v214, v214, v124
	v_mul_f32_e32 v215, v215, v125
	v_cvt_pk_bf16_f32 v217, v214, v215
	ds_write_b16 v1, v217 offset:6592
	ds_write_b16_d16_hi v1, v217 offset:6864
	v_fmamk_f32 v214, v199, 0x40c00000, v212
	v_fmamk_f32 v216, v201, 0xc0c00000, v213
	v_min_f32_e32 v214, v214, v216
	v_fmamk_f32 v215, v199, 0x40a00000, v212
	v_fmamk_f32 v216, v201, 0xc0a00000, v213
	v_min_f32_e32 v215, v215, v216
	v_exp_f32_e32 v214, v214
	v_exp_f32_e32 v215, v215
	s_nop 0
	v_mul_f32_e32 v214, v214, v126
	v_mul_f32_e32 v215, v215, v127
	v_cvt_pk_bf16_f32 v217, v214, v215
	ds_write_b16 v1, v217 offset:7136
	ds_write_b16_d16_hi v1, v217 offset:7408
	v_mov_b32_e32 v1, v2
